# combine -> GEMM: per-row-tile counters for the normalised activations (written through) instead of the grid barrier; GEMM wave 0 waits for its units' row tiles, invalidates once; the combine that also
# speedup vs baseline: 1.0446x; 1.0098x over previous
.LBB0_208:
	s_waitcnt vmcnt(15)
	v_mul_f32_e32 v0, v35, v35
	v_mul_f32_e32 v131, v37, v37
	v_fmac_f32_e32 v0, v34, v34
	v_fmac_f32_e32 v131, v36, v36
	v_add_f32_e32 v0, v0, v131
	s_waitcnt vmcnt(14)
	v_mul_f32_e32 v131, v39, v39
	v_mul_f32_e32 v184, v41, v41
	v_fmac_f32_e32 v131, v38, v38
	v_fmac_f32_e32 v184, v40, v40
	v_add_f32_e32 v131, v131, v184
	v_add_f32_e32 v0, v0, v131
	s_waitcnt vmcnt(13)
	v_mul_f32_e32 v131, v47, v47
	v_mul_f32_e32 v184, v49, v49
	v_fmac_f32_e32 v131, v46, v46
	v_fmac_f32_e32 v184, v48, v48
	v_add_f32_e32 v131, v131, v184
	v_add_f32_e32 v0, v0, v131
	v_mul_f32_e32 v131, v19, v19
	v_mul_f32_e32 v184, v21, v21
	v_fmac_f32_e32 v131, v18, v18
	v_fmac_f32_e32 v184, v20, v20
	v_add_f32_e32 v131, v131, v184
	v_mul_f32_e32 v184, v23, v23
	v_mul_f32_e32 v185, v25, v25
	v_fmac_f32_e32 v184, v22, v22
	v_fmac_f32_e32 v185, v24, v24
	v_add_f32_e32 v184, v184, v185
	v_add_f32_e32 v131, v131, v184
	v_mul_f32_e32 v184, v59, v59
	v_mul_f32_e32 v185, v61, v61
	v_fmac_f32_e32 v184, v58, v58
	v_fmac_f32_e32 v185, v60, v60
	v_add_f32_e32 v184, v184, v185
	v_mul_f32_e32 v185, v55, v55
	v_mul_f32_e32 v186, v57, v57
	v_fmac_f32_e32 v185, v54, v54
	v_fmac_f32_e32 v186, v56, v56
	v_add_f32_e32 v185, v185, v186
	v_add_f32_e32 v184, v184, v185
	v_mul_f32_e32 v185, v63, v63
	v_mul_f32_e32 v186, v65, v65
	v_fmac_f32_e32 v185, v62, v62
	v_fmac_f32_e32 v186, v64, v64
	v_add_f32_e32 v185, v185, v186
	v_add_f32_e32 v184, v184, v185
	v_mul_f32_e32 v185, v43, v43
	v_mul_f32_e32 v186, v45, v45
	v_fmac_f32_e32 v185, v42, v42
	v_fmac_f32_e32 v186, v44, v44
	v_add_f32_e32 v185, v185, v186
	v_add_f32_e32 v184, v184, v185
	v_mul_f32_e32 v185, v79, v79
	v_mul_f32_e32 v186, v81, v81
	v_fmac_f32_e32 v185, v78, v78
	v_fmac_f32_e32 v186, v80, v80
	v_add_f32_e32 v185, v185, v186
	v_mul_f32_e32 v186, v75, v75
	v_mul_f32_e32 v187, v77, v77
	v_fmac_f32_e32 v186, v74, v74
	v_fmac_f32_e32 v187, v76, v76
	v_add_f32_e32 v186, v186, v187
	v_add_f32_e32 v185, v185, v186
	v_mul_f32_e32 v186, v71, v71
	v_mul_f32_e32 v187, v73, v73
	v_fmac_f32_e32 v186, v70, v70
	v_fmac_f32_e32 v187, v72, v72
	v_add_f32_e32 v186, v186, v187
	v_add_f32_e32 v185, v185, v186
	v_mul_f32_e32 v186, v67, v67
	v_mul_f32_e32 v187, v69, v69
	v_fmac_f32_e32 v186, v66, v66
	v_fmac_f32_e32 v187, v68, v68
	v_add_f32_e32 v186, v186, v187
	v_add_f32_e32 v185, v185, v186
	ds_bpermute_b32 v187, v246, v185
	ds_bpermute_b32 v186, v246, v184
	v_mul_f32_e32 v220, v27, v27
	v_mul_f32_e32 v221, v29, v29
	v_fmac_f32_e32 v220, v26, v26
	v_fmac_f32_e32 v221, v28, v28
	s_waitcnt lgkmcnt(0)
	v_pk_add_f32 v[184:185], v[184:185], v[186:187]
	ds_bpermute_b32 v187, v247, v185
	ds_bpermute_b32 v186, v247, v184
	v_add_f32_e32 v220, v220, v221
	v_add_f32_e32 v131, v131, v220
	v_mul_f32_e32 v220, v31, v31
	v_mul_f32_e32 v221, v33, v33
	s_waitcnt lgkmcnt(0)
	v_pk_add_f32 v[184:185], v[184:185], v[186:187]
	ds_bpermute_b32 v187, v248, v185
	ds_bpermute_b32 v186, v248, v184
	v_fmac_f32_e32 v220, v30, v30
	v_fmac_f32_e32 v221, v32, v32
	v_add_f32_e32 v220, v220, v221
	v_add_f32_e32 v223, v131, v220
	s_waitcnt lgkmcnt(0)
	v_pk_add_f32 v[184:185], v[184:185], v[186:187]
	ds_bpermute_b32 v187, v249, v185
	ds_bpermute_b32 v186, v249, v184
	s_waitcnt vmcnt(12)
	v_pk_mul_f32 v[220:221], v[52:53], v[52:53]
	v_pk_mul_f32 v[238:239], v[50:51], v[50:51]
	s_mov_b32 s4, 0x358637bd
	v_pk_mov_b32 v[240:241], v[238:239], v[220:221] op_sel:[1,0]
	s_waitcnt lgkmcnt(0)
	v_pk_add_f32 v[184:185], v[184:185], v[186:187]
	ds_bpermute_b32 v187, v250, v185
	ds_bpermute_b32 v186, v250, v184
	v_mov_b32_e32 v239, v221
	v_pk_add_f32 v[220:221], v[240:241], v[238:239]
	s_mov_b32 s6, 0x3a800000
	v_add_f32_e32 v131, v220, v221
	s_waitcnt lgkmcnt(0)
	v_pk_add_f32 v[184:185], v[184:185], v[186:187]
	ds_bpermute_b32 v187, v251, v185
	ds_bpermute_b32 v186, v251, v184
	v_mov_b64_e32 v[220:221], s[4:5]
	v_add_f32_e32 v222, v0, v131
	s_waitcnt vmcnt(2)
	v_pk_add_f32 v[114:115], v[114:115], 1.0 op_sel_hi:[1,0]
	v_pk_add_f32 v[126:127], v[126:127], 1.0 op_sel_hi:[1,0]
	s_waitcnt lgkmcnt(0)
	v_pk_add_f32 v[184:185], v[184:185], v[186:187]
	v_pk_add_f32 v[116:117], v[116:117], 1.0 op_sel_hi:[1,0]
	v_pk_fma_f32 v[184:185], v[184:185], s[6:7], v[220:221] op_sel_hi:[1,0,0]
	v_pk_add_f32 v[128:129], v[128:129], 1.0 op_sel_hi:[1,0]
	v_mul_f32_e32 v0, 0x4b800000, v185
	v_cmp_gt_f32_e32 vcc, s69, v185
	v_pk_add_f32 v[122:123], v[122:123], 1.0 op_sel_hi:[1,0]
	v_lshl_add_u64 v[240:241], v[146:147], 0, s[38:39]
	v_cndmask_b32_e32 v0, v185, v0, vcc
	v_rsq_f32_e32 v0, v0
	v_pk_add_f32 v[124:125], v[124:125], 1.0 op_sel_hi:[1,0]
	v_pk_add_f32 v[118:119], v[118:119], 1.0 op_sel_hi:[1,0]
	v_pk_add_f32 v[120:121], v[120:121], 1.0 op_sel_hi:[1,0]
	v_mul_f32_e32 v131, 0x45800000, v0
	v_cndmask_b32_e32 v0, v0, v131, vcc
	v_pk_mul_f32 v[66:67], v[66:67], v[0:1] op_sel_hi:[1,0]
	v_pk_mul_f32 v[80:81], v[80:81], v[0:1] op_sel_hi:[1,0]
	v_pk_mul_f32 v[66:67], v[82:83], v[66:67]
	v_pk_mul_f32 v[78:79], v[78:79], v[0:1] op_sel_hi:[1,0]
	s_waitcnt vmcnt(0)
	v_pk_fma_f32 v[66:67], v[114:115], v[66:67], v[86:87]
	v_pk_mul_f32 v[76:77], v[76:77], v[0:1] op_sel_hi:[1,0]
	v_pk_mul_f32 v[74:75], v[74:75], v[0:1] op_sel_hi:[1,0]
	v_pk_mul_f32 v[72:73], v[72:73], v[0:1] op_sel_hi:[1,0]
	v_pk_mul_f32 v[70:71], v[70:71], v[0:1] op_sel_hi:[1,0]
	v_pk_mul_f32 v[68:69], v[68:69], v[0:1] op_sel_hi:[1,0]
	v_bfe_u32 v0, v66, 16, 1
	v_pk_mul_f32 v[78:79], v[106:107], v[78:79]
	v_pk_mul_f32 v[68:69], v[84:85], v[68:69]
	v_add3_u32 v0, v66, v0, s60
	v_bfe_u32 v66, v67, 16, 1
	v_pk_fma_f32 v[78:79], v[126:127], v[78:79], v[110:111]
	v_pk_fma_f32 v[68:69], v[116:117], v[68:69], v[88:89]
	v_lshrrev_b32_e32 v0, 16, v0
	v_add3_u32 v66, v67, v66, s60
	v_bfe_u32 v131, v78, 16, 1
	v_and_or_b32 v66, v66, s85, v0
	v_bfe_u32 v0, v68, 16, 1
	v_pk_mul_f32 v[80:81], v[108:109], v[80:81]
	v_add3_u32 v78, v78, v131, s60
	v_bfe_u32 v131, v79, 16, 1
	v_add3_u32 v0, v68, v0, s60
	v_mul_f32_e32 v68, 0x4b800000, v184
	v_cmp_gt_f32_e32 vcc, s69, v184
	v_pk_fma_f32 v[80:81], v[128:129], v[80:81], v[112:113]
	v_lshrrev_b32_e32 v78, 16, v78
	v_add3_u32 v79, v79, v131, s60
	v_cndmask_b32_e32 v68, v184, v68, vcc
	v_and_or_b32 v78, v79, s85, v78
	v_bfe_u32 v79, v80, 16, 1
	v_rsq_f32_e32 v68, v68
	v_add3_u32 v79, v80, v79, s60
	v_bfe_u32 v80, v81, 16, 1
	v_lshrrev_b32_e32 v79, 16, v79
	v_add3_u32 v80, v81, v80, s60
	v_pk_mul_f32 v[74:75], v[98:99], v[74:75]
	v_bfe_u32 v67, v69, 16, 1
	v_and_or_b32 v79, v80, s85, v79
	v_pk_fma_f32 v[74:75], v[122:123], v[74:75], v[102:103]
	v_lshrrev_b32_e32 v0, 16, v0
	v_add3_u32 v67, v69, v67, s60
	global_store_dwordx2 v[240:241], v[78:79], off sc1
	v_bfe_u32 v78, v74, 16, 1
	v_and_or_b32 v67, v67, s85, v0
	v_mul_f32_e32 v0, 0x45800000, v68
	v_pk_mul_f32 v[76:77], v[100:101], v[76:77]
	v_add3_u32 v74, v74, v78, s60
	v_bfe_u32 v78, v75, 16, 1
	v_cndmask_b32_e32 v0, v68, v0, vcc
	v_pk_fma_f32 v[76:77], v[124:125], v[76:77], v[104:105]
	v_lshrrev_b32_e32 v74, 16, v74
	v_add3_u32 v75, v75, v78, s60
	v_pk_mul_f32 v[58:59], v[58:59], v[0:1] op_sel_hi:[1,0]
	v_and_or_b32 v74, v75, s85, v74
	v_bfe_u32 v75, v76, 16, 1
	v_pk_mul_f32 v[58:59], v[106:107], v[58:59]
	v_add3_u32 v75, v76, v75, s60
	v_bfe_u32 v76, v77, 16, 1
	v_pk_fma_f32 v[58:59], v[126:127], v[58:59], v[110:111]
	v_lshrrev_b32_e32 v75, 16, v75
	v_add3_u32 v76, v77, v76, s60
	v_pk_mul_f32 v[70:71], v[90:91], v[70:71]
	global_store_dwordx2 v[240:241], v[66:67], off offset:1536 sc1
	v_pk_mul_f32 v[60:61], v[60:61], v[0:1] op_sel_hi:[1,0]
	v_bfe_u32 v66, v58, 16, 1
	v_and_or_b32 v75, v76, s85, v75
	v_pk_fma_f32 v[70:71], v[118:119], v[70:71], v[94:95]
	v_pk_mul_f32 v[60:61], v[108:109], v[60:61]
	v_add3_u32 v58, v58, v66, s60
	v_bfe_u32 v66, v59, 16, 1
	global_store_dwordx2 v[240:241], v[74:75], off offset:512 sc1
	v_bfe_u32 v74, v70, 16, 1
	v_pk_fma_f32 v[60:61], v[128:129], v[60:61], v[112:113]
	v_lshrrev_b32_e32 v58, 16, v58
	v_add3_u32 v59, v59, v66, s60
	v_pk_mul_f32 v[72:73], v[92:93], v[72:73]
	v_add3_u32 v70, v70, v74, s60
	v_bfe_u32 v74, v71, 16, 1
	v_and_or_b32 v58, v59, s85, v58
	v_bfe_u32 v59, v60, 16, 1
	v_pk_fma_f32 v[72:73], v[120:121], v[72:73], v[96:97]
	v_lshrrev_b32_e32 v70, 16, v70
	v_add3_u32 v71, v71, v74, s60
	v_add3_u32 v59, v60, v59, s60
	v_bfe_u32 v60, v61, 16, 1
	v_and_or_b32 v70, v71, s85, v70
	v_bfe_u32 v71, v72, 16, 1
	v_lshrrev_b32_e32 v59, 16, v59
	v_add3_u32 v60, v61, v60, s60
	v_add3_u32 v71, v72, v71, s60
	v_bfe_u32 v72, v73, 16, 1
	v_and_or_b32 v59, v60, s85, v59
	v_lshl_add_u64 v[60:61], s[34:35], 0, v[144:145]
	s_mov_b32 s4, 0x5c00000
	v_pk_mul_f32 v[54:55], v[54:55], v[0:1] op_sel_hi:[1,0]
	v_lshrrev_b32_e32 v71, 16, v71
	v_add3_u32 v72, v73, v72, s60
	v_add_co_u32_e32 v66, vcc, s4, v60
	v_pk_mul_f32 v[54:55], v[98:99], v[54:55]
	v_and_or_b32 v71, v72, s85, v71
	v_addc_co_u32_e32 v67, vcc, 0, v61, vcc
	v_pk_fma_f32 v[54:55], v[122:123], v[54:55], v[102:103]
	global_store_dwordx2 v[240:241], v[70:71], off offset:1024 sc1
	global_store_dwordx2 v[66:67], v[58:59], off offset:2048 sc1
	v_pk_mul_f32 v[56:57], v[56:57], v[0:1] op_sel_hi:[1,0]
	v_bfe_u32 v58, v54, 16, 1
	v_pk_mul_f32 v[56:57], v[100:101], v[56:57]
	v_add3_u32 v54, v54, v58, s60
	v_bfe_u32 v58, v55, 16, 1
	v_pk_fma_f32 v[56:57], v[124:125], v[56:57], v[104:105]
	v_lshrrev_b32_e32 v54, 16, v54
	v_add3_u32 v55, v55, v58, s60
	v_and_or_b32 v54, v55, s85, v54
	v_bfe_u32 v55, v56, 16, 1
	v_add3_u32 v55, v56, v55, s60
	v_bfe_u32 v56, v57, 16, 1
	v_lshrrev_b32_e32 v55, 16, v55
	v_add3_u32 v56, v57, v56, s60
	ds_bpermute_b32 v239, v246, v223
	ds_bpermute_b32 v238, v246, v222
	v_and_or_b32 v55, v56, s85, v55
	v_pk_mul_f32 v[56:57], v[62:63], v[0:1] op_sel_hi:[1,0]
	global_store_dwordx2 v[66:67], v[54:55], off offset:2560 sc1
	v_pk_mul_f32 v[56:57], v[90:91], v[56:57]
	v_pk_mul_f32 v[54:55], v[64:65], v[0:1] op_sel_hi:[1,0]
	v_pk_fma_f32 v[56:57], v[118:119], v[56:57], v[94:95]
	v_pk_mul_f32 v[54:55], v[92:93], v[54:55]
	v_bfe_u32 v58, v56, 16, 1
	v_add3_u32 v56, v56, v58, s60
	v_bfe_u32 v58, v57, 16, 1
	v_add3_u32 v57, v57, v58, s60
	s_waitcnt lgkmcnt(0)
	v_pk_add_f32 v[58:59], v[222:223], v[238:239]
	ds_bpermute_b32 v63, v247, v59
	ds_bpermute_b32 v62, v247, v58
	v_pk_fma_f32 v[54:55], v[120:121], v[54:55], v[96:97]
	v_lshrrev_b32_e32 v56, 16, v56
	v_and_or_b32 v56, v57, s85, v56
	v_bfe_u32 v57, v54, 16, 1
	v_add3_u32 v54, v54, v57, s60
	v_bfe_u32 v57, v55, 16, 1
	v_lshrrev_b32_e32 v54, 16, v54
	v_add3_u32 v55, v55, v57, s60
	v_and_or_b32 v57, v55, s85, v54
	s_waitcnt lgkmcnt(0)
	v_pk_add_f32 v[54:55], v[58:59], v[62:63]
	global_store_dwordx2 v[66:67], v[56:57], off offset:3072 sc1
	ds_bpermute_b32 v57, v248, v55
	ds_bpermute_b32 v56, v248, v54
	v_pk_mul_f32 v[42:43], v[42:43], v[0:1] op_sel_hi:[1,0]
	v_pk_mul_f32 v[44:45], v[44:45], v[0:1] op_sel_hi:[1,0]
	v_pk_mul_f32 v[42:43], v[82:83], v[42:43]
	v_pk_mul_f32 v[44:45], v[84:85], v[44:45]
	s_waitcnt lgkmcnt(0)
	v_pk_add_f32 v[54:55], v[54:55], v[56:57]
	ds_bpermute_b32 v57, v249, v55
	ds_bpermute_b32 v56, v249, v54
	v_pk_fma_f32 v[42:43], v[114:115], v[42:43], v[86:87]
	v_pk_fma_f32 v[44:45], v[116:117], v[44:45], v[88:89]
	v_bfe_u32 v0, v42, 16, 1
	v_add3_u32 v0, v42, v0, s60
	s_waitcnt lgkmcnt(0)
	v_pk_add_f32 v[54:55], v[54:55], v[56:57]
	ds_bpermute_b32 v57, v250, v55
	ds_bpermute_b32 v56, v250, v54
	v_bfe_u32 v42, v43, 16, 1
	v_lshrrev_b32_e32 v0, 16, v0
	v_add3_u32 v42, v43, v42, s60
	v_and_or_b32 v42, v42, s85, v0
	s_waitcnt lgkmcnt(0)
	v_pk_add_f32 v[54:55], v[54:55], v[56:57]
	ds_bpermute_b32 v57, v251, v55
	ds_bpermute_b32 v56, v251, v54
	v_bfe_u32 v0, v44, 16, 1
	v_add3_u32 v0, v44, v0, s60
	v_bfe_u32 v43, v45, 16, 1
	v_lshrrev_b32_e32 v0, 16, v0
	s_waitcnt lgkmcnt(0)
	v_pk_add_f32 v[54:55], v[54:55], v[56:57]
	v_add3_u32 v43, v45, v43, s60
	v_pk_fma_f32 v[54:55], v[54:55], s[6:7], v[220:221] op_sel_hi:[1,0,0]
	v_and_or_b32 v43, v43, s85, v0
	v_mul_f32_e32 v44, 0x4b800000, v55
	v_cmp_gt_f32_e32 vcc, s69, v55
	global_store_dwordx2 v[66:67], v[42:43], off offset:3584 sc1
	s_mov_b32 s4, 0x5c01000
	v_cndmask_b32_e32 v44, v55, v44, vcc
	v_rsq_f32_e32 v44, v44
	s_add_u32 s26, s26, s62
	s_addc_u32 s27, s27, s63
	v_readlane_b32 s6, v254, 62
	v_mul_f32_e32 v0, 0x45800000, v44
	v_cndmask_b32_e32 v0, v44, v0, vcc
	v_pk_mul_f32 v[18:19], v[18:19], v[0:1] op_sel_hi:[1,0]
	v_pk_mul_f32 v[20:21], v[20:21], v[0:1] op_sel_hi:[1,0]
	v_pk_mul_f32 v[18:19], v[106:107], v[18:19]
	v_pk_mul_f32 v[20:21], v[108:109], v[20:21]
	v_pk_fma_f32 v[18:19], v[126:127], v[18:19], v[110:111]
	v_pk_fma_f32 v[20:21], v[128:129], v[20:21], v[112:113]
	v_bfe_u32 v42, v18, 16, 1
	v_add3_u32 v18, v18, v42, s60
	v_bfe_u32 v42, v19, 16, 1
	v_lshrrev_b32_e32 v18, 16, v18
	v_add3_u32 v19, v19, v42, s60
	v_and_or_b32 v18, v19, s85, v18
	v_bfe_u32 v19, v20, 16, 1
	v_add3_u32 v19, v20, v19, s60
	v_bfe_u32 v20, v21, 16, 1
	v_lshrrev_b32_e32 v19, 16, v19
	v_add3_u32 v20, v21, v20, s60
	v_pk_mul_f32 v[22:23], v[22:23], v[0:1] op_sel_hi:[1,0]
	v_and_or_b32 v19, v20, s85, v19
	v_add_co_u32_e32 v20, vcc, s4, v60
	v_pk_mul_f32 v[22:23], v[98:99], v[22:23]
	s_nop 0
	v_addc_co_u32_e32 v21, vcc, 0, v61, vcc
	v_pk_fma_f32 v[22:23], v[122:123], v[22:23], v[102:103]
	global_store_dwordx2 v[20:21], v[18:19], off sc1
	v_pk_mul_f32 v[18:19], v[24:25], v[0:1] op_sel_hi:[1,0]
	v_bfe_u32 v24, v22, 16, 1
	v_pk_mul_f32 v[18:19], v[100:101], v[18:19]
	v_add3_u32 v22, v22, v24, s60
	v_bfe_u32 v24, v23, 16, 1
	v_pk_fma_f32 v[18:19], v[124:125], v[18:19], v[104:105]
	v_lshrrev_b32_e32 v22, 16, v22
	v_add3_u32 v23, v23, v24, s60
	v_and_or_b32 v22, v23, s85, v22
	v_bfe_u32 v23, v18, 16, 1
	v_add3_u32 v18, v18, v23, s60
	v_bfe_u32 v23, v19, 16, 1
	v_lshrrev_b32_e32 v18, 16, v18
	v_add3_u32 v19, v19, v23, s60
	v_and_or_b32 v23, v19, s85, v18
	global_store_dwordx2 v[20:21], v[22:23], off offset:512 sc1
	v_pk_mul_f32 v[22:23], v[26:27], v[0:1] op_sel_hi:[1,0]
	v_pk_mul_f32 v[18:19], v[28:29], v[0:1] op_sel_hi:[1,0]
	v_pk_mul_f32 v[22:23], v[90:91], v[22:23]
	v_pk_mul_f32 v[18:19], v[92:93], v[18:19]
	v_pk_fma_f32 v[22:23], v[118:119], v[22:23], v[94:95]
	v_pk_fma_f32 v[18:19], v[120:121], v[18:19], v[96:97]
	v_bfe_u32 v24, v22, 16, 1
	v_add3_u32 v22, v22, v24, s60
	v_bfe_u32 v24, v23, 16, 1
	v_lshrrev_b32_e32 v22, 16, v22
	v_add3_u32 v23, v23, v24, s60
	v_and_or_b32 v22, v23, s85, v22
	v_bfe_u32 v23, v18, 16, 1
	v_add3_u32 v18, v18, v23, s60
	v_bfe_u32 v23, v19, 16, 1
	v_lshrrev_b32_e32 v18, 16, v18
	v_add3_u32 v19, v19, v23, s60
	v_and_or_b32 v23, v19, s85, v18
	global_store_dwordx2 v[20:21], v[22:23], off offset:1024 sc1
	v_pk_mul_f32 v[22:23], v[30:31], v[0:1] op_sel_hi:[1,0]
	v_pk_mul_f32 v[18:19], v[32:33], v[0:1] op_sel_hi:[1,0]
	v_pk_mul_f32 v[22:23], v[82:83], v[22:23]
	v_cmp_gt_f32_e32 vcc, s69, v54
	v_pk_fma_f32 v[22:23], v[114:115], v[22:23], v[86:87]
	v_pk_mul_f32 v[18:19], v[84:85], v[18:19]
	v_bfe_u32 v0, v22, 16, 1
	v_add3_u32 v0, v22, v0, s60
	v_bfe_u32 v22, v23, 16, 1
	v_add3_u32 v22, v23, v22, s60
	v_mul_f32_e32 v23, 0x4b800000, v54
	v_cndmask_b32_e32 v23, v54, v23, vcc
	v_pk_fma_f32 v[18:19], v[116:117], v[18:19], v[88:89]
	v_lshrrev_b32_e32 v0, 16, v0
	v_rsq_f32_e32 v24, v23
	v_and_or_b32 v22, v22, s85, v0
	v_bfe_u32 v0, v18, 16, 1
	v_add3_u32 v0, v18, v0, s60
	v_bfe_u32 v18, v19, 16, 1
	v_lshrrev_b32_e32 v0, 16, v0
	v_add3_u32 v18, v19, v18, s60
	v_and_or_b32 v23, v18, s85, v0
	v_mul_f32_e32 v0, 0x45800000, v24
	v_cndmask_b32_e32 v0, v24, v0, vcc
	global_store_dwordx2 v[20:21], v[22:23], off offset:1536 sc1
	v_pk_mul_f32 v[22:23], v[34:35], v[0:1] op_sel_hi:[1,0]
	v_pk_mul_f32 v[18:19], v[36:37], v[0:1] op_sel_hi:[1,0]
	v_pk_mul_f32 v[22:23], v[106:107], v[22:23]
	v_pk_mul_f32 v[18:19], v[108:109], v[18:19]
	v_pk_fma_f32 v[22:23], v[126:127], v[22:23], v[110:111]
	v_pk_fma_f32 v[18:19], v[128:129], v[18:19], v[112:113]
	v_bfe_u32 v24, v22, 16, 1
	v_add3_u32 v22, v22, v24, s60
	v_bfe_u32 v24, v23, 16, 1
	v_lshrrev_b32_e32 v22, 16, v22
	v_add3_u32 v23, v23, v24, s60
	v_and_or_b32 v22, v23, s85, v22
	v_bfe_u32 v23, v18, 16, 1
	v_add3_u32 v18, v18, v23, s60
	v_bfe_u32 v23, v19, 16, 1
	v_lshrrev_b32_e32 v18, 16, v18
	v_add3_u32 v19, v19, v23, s60
	v_and_or_b32 v23, v19, s85, v18
	global_store_dwordx2 v[20:21], v[22:23], off offset:2048 sc1
	v_pk_mul_f32 v[22:23], v[38:39], v[0:1] op_sel_hi:[1,0]
	v_pk_mul_f32 v[18:19], v[40:41], v[0:1] op_sel_hi:[1,0]
	v_pk_mul_f32 v[22:23], v[98:99], v[22:23]
	v_pk_mul_f32 v[18:19], v[100:101], v[18:19]
	v_pk_fma_f32 v[22:23], v[122:123], v[22:23], v[102:103]
	v_pk_fma_f32 v[18:19], v[124:125], v[18:19], v[104:105]
	v_bfe_u32 v24, v22, 16, 1
	v_add3_u32 v22, v22, v24, s60
	v_bfe_u32 v24, v23, 16, 1
	v_lshrrev_b32_e32 v22, 16, v22
	v_add3_u32 v23, v23, v24, s60
	v_and_or_b32 v22, v23, s85, v22
	v_bfe_u32 v23, v18, 16, 1
	v_add3_u32 v18, v18, v23, s60
	v_bfe_u32 v23, v19, 16, 1
	v_lshrrev_b32_e32 v18, 16, v18
	v_add3_u32 v19, v19, v23, s60
	v_and_or_b32 v23, v19, s85, v18
	global_store_dwordx2 v[20:21], v[22:23], off offset:2560 sc1
	v_pk_mul_f32 v[22:23], v[46:47], v[0:1] op_sel_hi:[1,0]
	v_pk_mul_f32 v[18:19], v[48:49], v[0:1] op_sel_hi:[1,0]
	v_pk_mul_f32 v[22:23], v[90:91], v[22:23]
	v_pk_mul_f32 v[18:19], v[92:93], v[18:19]
	v_pk_fma_f32 v[22:23], v[118:119], v[22:23], v[94:95]
	v_pk_fma_f32 v[18:19], v[120:121], v[18:19], v[96:97]
	v_bfe_u32 v24, v22, 16, 1
	v_add3_u32 v22, v22, v24, s60
	v_bfe_u32 v24, v23, 16, 1
	v_lshrrev_b32_e32 v22, 16, v22
	v_add3_u32 v23, v23, v24, s60
	v_and_or_b32 v22, v23, s85, v22
	v_bfe_u32 v23, v18, 16, 1
	v_add3_u32 v18, v18, v23, s60
	v_bfe_u32 v23, v19, 16, 1
	v_lshrrev_b32_e32 v18, 16, v18
	v_add3_u32 v19, v19, v23, s60
	v_and_or_b32 v23, v19, s85, v18
	global_store_dwordx2 v[20:21], v[22:23], off offset:3072 sc1
	v_pk_mul_f32 v[22:23], v[50:51], v[0:1] op_sel_hi:[1,0]
	v_readlane_b32 s4, v254, 60
	v_pk_mul_f32 v[22:23], v[82:83], v[22:23]
	v_pk_mul_f32 v[18:19], v[52:53], v[0:1] op_sel_hi:[1,0]
	v_pk_fma_f32 v[22:23], v[114:115], v[22:23], v[86:87]
	v_readlane_b32 s5, v254, 61
	v_bfe_u32 v0, v22, 16, 1
	s_add_u32 s22, s22, s4
	v_pk_mul_f32 v[18:19], v[84:85], v[18:19]
	v_add3_u32 v0, v22, v0, s60
	v_bfe_u32 v22, v23, 16, 1
	s_addc_u32 s23, s23, s5
	v_pk_fma_f32 v[18:19], v[116:117], v[18:19], v[88:89]
	v_lshrrev_b32_e32 v0, 16, v0
	v_add3_u32 v22, v23, v22, s60
	v_readlane_b32 s7, v254, 63
	s_add_u32 s34, s34, s6
	v_and_or_b32 v22, v22, s85, v0
	v_bfe_u32 v0, v18, 16, 1
	s_addc_u32 s35, s35, s7
	v_add3_u32 v0, v18, v0, s60
	v_bfe_u32 v18, v19, 16, 1
	s_add_u32 s36, s36, s6
	v_lshrrev_b32_e32 v0, 16, v0
	v_add3_u32 v18, v19, v18, s60
	s_addc_u32 s37, s37, s7
	v_and_or_b32 v23, v18, s85, v0
	s_cmpk_lt_i32 s26, 0x2000
	v_lshl_add_u64 v[148:149], v[148:149], 0, s[4:5]
	global_store_dwordx2 v[20:21], v[22:23], off offset:3584 sc1
	s_cbranch_scc0 .LBB0_313

.LBB0_336:
	s_waitcnt vmcnt(0)
	s_waitcnt lgkmcnt(0)
	s_barrier
	s_and_saveexec_b64 s[4:5], s[8:9]
	v_readlane_b32 s51, v255, 33
	v_readlane_b32 s50, v255, 11
	s_cbranch_execz .LBB0_388
	v_readlane_b32 s1, v255, 0
	s_nop 3
	s_lshr_b32 s1, s1, 3
	s_lshl_b32 s1, s1, 4
	s_add_u32 s1, s1, 0xe803e00
	s_waitcnt lgkmcnt(0)
	s_add_u32 s2, s6, s1
	s_addc_u32 s3, s7, 0
	v_mov_b32_e32 v0, 1
	v_mov_b32_e32 v2, 0
	global_atomic_add v2, v0, s[2:3]
	v_mov_b32_e32 v0, 0x2017c
	v_mov_b32_e32 v2, 8
	ds_add_u32 v0, v2
	v_readlane_b32 s1, v255, 21
	s_nop 3
	s_cmp_lg_u32 s1, 1
	s_cbranch_scc1 .LBB0_388
	s_cmp_lg_u32 s51, 0
	s_cbranch_scc1 .LBB0_388
	v_readlane_b32 s1, v254, 51
	s_waitcnt vmcnt(0) expcnt(0) lgkmcnt(0)
	s_and_b32 s0, s0, 15
	v_mov_b32_e32 v0, s1
	ds_read_b32 v3, v0
	v_readlane_b32 s1, v254, 52
	s_waitcnt lgkmcnt(0)
	v_cmp_ne_u32_e32 vcc, 0, v3
	v_mov_b32_e32 v0, s1
	ds_read_b32 v2, v0
	s_cbranch_vccnz .LBB0_352
	s_add_u32 s8, s6, 0xe800200
	s_addc_u32 s9, s7, 0
	s_add_u32 s10, s6, 0xe800400
	s_addc_u32 s11, s7, 0
	s_add_u32 s14, s6, 0xe800500
	s_addc_u32 s15, s7, 0
	s_add_u32 s16, s6, 0xe800600
	s_addc_u32 s17, s7, 0
	s_add_u32 s18, s6, 0xe800700
	s_addc_u32 s19, s7, 0
	s_add_u32 s20, s6, 0xe800800
	s_addc_u32 s21, s7, 0
	s_add_u32 s22, s6, 0xe800900
	s_addc_u32 s23, s7, 0
	s_add_u32 s24, s6, 0xe800a00
	s_addc_u32 s25, s7, 0
	s_add_u32 s26, s6, 0xe800b00
	s_addc_u32 s27, s7, 0
	s_add_u32 s28, s6, 0xe800c00
	s_addc_u32 s29, s7, 0
	s_add_u32 s30, s6, 0xe800d00
	s_addc_u32 s31, s7, 0
	s_add_u32 s34, s6, 0xe800e00
	s_addc_u32 s35, s7, 0
	s_add_u32 s36, s6, 0xe800f00
	s_addc_u32 s37, s7, 0
	s_add_u32 s38, s6, 0xe801000
	s_addc_u32 s39, s7, 0
	s_add_u32 s40, s6, 0xe801100
	s_addc_u32 s41, s7, 0
	s_add_u32 s42, s6, 0xe801200
	s_addc_u32 s43, s7, 0
	s_add_u32 s46, s6, 0xe801300
	s_addc_u32 s47, s7, 0
	s_mov_b32 s1, 1
	s_branch .LBB0_340

.LBB0_388:
	s_or_b64 exec, exec, s[4:5]
	s_cmp_eq_u32 s51, 1
	s_mov_b64 s[4:5], -1
	s_waitcnt lgkmcnt(0)
	s_barrier
	s_cmp_lg_u32 s86, 0
	s_cbranch_scc1 .Lhf_done
	s_load_dwordx2 s[6:7], s[66:67], 0x100
	v_mov_b32_e32 v0, 0x2017c
	ds_read_b32 v2, v0
	v_readlane_b32 s0, v255, 0
	s_nop 3
	s_and_b32 s1, s0, 7
	s_lshr_b32 s2, s0, 3
	s_cmp_eq_u32 s51, 1
	s_cbranch_scc1 .Lhf_in
	s_mul_i32 s3, s1, 88
	s_add_i32 s3, s3, s2
	s_mul_i32 s8, s3, 0x5d18
	s_lshr_b32 s8, s8, 22
	s_mul_i32 s14, s8, 0xb0
	s_sub_i32 s14, s3, s14
	s_and_b32 s14, s14, 7
	s_lshl_b32 s8, s8, 3
	s_add_i32 s8, s8, s14
	s_add_i32 s15, s3, 32
	s_mul_i32 s9, s15, 0x5d18
	s_lshr_b32 s9, s9, 22
	s_mul_i32 s14, s9, 0xb0
	s_sub_i32 s14, s15, s14
	s_and_b32 s14, s14, 7
	s_lshl_b32 s9, s9, 3
	s_add_i32 s9, s9, s14
	s_add_i32 s15, s3, 64
	s_cmp_lt_u32 s0, 0xc0
	s_cselect_b32 s15, s15, s3
	s_mul_i32 s10, s15, 0x5d18
	s_lshr_b32 s10, s10, 22
	s_mul_i32 s14, s10, 0xb0
	s_sub_i32 s14, s15, s14
	s_and_b32 s14, s14, 7
	s_lshl_b32 s10, s10, 3
	s_add_i32 s10, s10, s14
	s_branch .Lhf_poll
.Lhf_in:
	s_lshl_b32 s8, s1, 2
	s_and_b32 s2, s2, 3
	s_add_i32 s8, s8, s2
	s_mov_b32 s9, s8
	s_mov_b32 s10, s8
.Lhf_poll:
	s_lshl_b32 s8, s8, 4
	s_lshl_b32 s9, s9, 4
	s_lshl_b32 s10, s10, 4
	v_mov_b32_e32 v3, s8
	v_mov_b32_e32 v4, s9
	v_mov_b32_e32 v5, s10
	s_waitcnt lgkmcnt(0)
	s_add_u32 s6, s6, 0xe803e00
	s_addc_u32 s7, s7, 0
.Lhf_loop:
	global_load_dword v6, v3, s[6:7] sc1
	global_load_dword v7, v4, s[6:7] sc1
	global_load_dword v8, v5, s[6:7] sc1
	s_waitcnt vmcnt(0)
	v_min3_u32 v6, v6, v7, v8
	v_cmp_le_u32_e32 vcc, v2, v6
	s_cbranch_vccnz .Lhf_rel
	s_sleep 2
	s_branch .Lhf_loop
.Lhf_rel:
	buffer_inv sc1
	s_waitcnt vmcnt(0)
.Lhf_done:
	s_barrier
	s_cmp_eq_u32 s51, 1
	s_cbranch_scc1 .LBB0_408
	s_mov_b64 s[8:9], s[66:67]
	v_mov_b32_e32 v0, v1
	s_load_dwordx2 s[10:11], s[8:9], 0x100
	v_mbcnt_lo_u32_b32 v0, -1, v0
	v_mbcnt_hi_u32_b32 v144, -1, v0
	v_readlane_b32 s0, v254, 8
	v_add_u32_e32 v0, s86, v144
	v_readlane_b32 s1, v254, 9
	s_lshr_b32 s52, s51, 1
	v_readfirstlane_b32 s4, v0
	s_andn2_b64 vcc, exec, s[0:1]
	v_readlane_b32 s0, v255, 16
	s_ashr_i32 s30, s4, 6
	s_add_i32 s52, s52, s0
	s_cbranch_vccnz .LBB0_410
	v_lshlrev_b32_e32 v2, 4, v0
	v_add_u32_e32 v3, 0x2000, v2
	v_ashrrev_i32_e32 v4, 31, v3
	v_lshrrev_b32_e32 v4, 22, v4
	v_add_u32_e32 v4, v3, v4
	v_ashrrev_i32_e32 v10, 10, v4
	v_mul_i32_i24_e32 v4, 0x400, v10
	v_sub_u32_e32 v3, v3, v4
	v_lshrrev_b32_e32 v4, 4, v3
	v_bitop3_b32 v3, v4, v3, 32 bitop3:0x6c
	v_ashrrev_i32_e32 v4, 31, v3
	v_lshrrev_b32_e32 v4, 26, v4
	v_add_u32_e32 v4, v3, v4
	v_lshlrev_b32_e32 v5, 3, v10
	v_ashrrev_i32_e32 v11, 6, v4
	v_and_b32_e32 v5, -16, v5
	v_add_u32_e32 v5, v11, v5
	v_and_b32_e32 v6, 3, v11
	s_mov_b32 s6, 0x1fffe0
	v_lshrrev_b32_e32 v7, 2, v5
	v_lshlrev_b32_e32 v8, 1, v5
	v_and_b32_e32 v4, 0xc0, v4
	v_and_or_b32 v6, v5, s6, v6
	v_and_b32_e32 v7, 4, v7
	v_and_b32_e32 v8, 24, v8
	v_sub_u32_e32 v3, v3, v4
	v_or3_b32 v6, v6, v7, v8
	v_lshlrev_b32_e32 v7, 5, v10
	v_ashrrev_i16_sdwa v3, v236, sext(v3) dst_sel:DWORD dst_unused:UNUSED_PAD src0_sel:DWORD src1_sel:BYTE_0
	v_and_b32_e32 v7, 32, v7
	v_bfe_i32 v12, v3, 0, 16
	v_add_lshl_u32 v3, v7, v12, 1
	v_lshl_add_u32 v130, v6, 11, v3
	v_lshl_add_u32 v132, v5, 11, v3
	v_bfe_i32 v3, v0, 27, 1
	v_lshrrev_b32_e32 v3, 22, v3
	v_add_u32_e32 v3, v2, v3
	v_and_b32_e32 v3, 0xfffffc00, v3
	v_sub_u32_e32 v2, v2, v3
	v_lshrrev_b32_e32 v3, 4, v2
	v_ashrrev_i32_e32 v4, 31, v0
	v_bitop3_b32 v2, v3, v2, 32 bitop3:0x6c
	v_lshrrev_b32_e32 v4, 26, v4
	v_ashrrev_i32_e32 v3, 31, v2
	v_add_u32_e32 v0, v0, v4
	v_lshrrev_b32_e32 v3, 26, v3
	v_ashrrev_i32_e32 v14, 6, v0
	v_add_u32_e32 v3, v2, v3
	v_lshlrev_b32_e32 v0, 3, v14
	v_ashrrev_i32_e32 v13, 6, v3
	v_and_b32_e32 v0, -16, v0
	s_waitcnt lgkmcnt(0)
	s_add_u32 s0, s10, 0x5c00000
	v_add_u32_e32 v4, v13, v0
	s_addc_u32 s1, s11, 0
	s_mul_i32 s2, s52, 0xb00000
	v_and_b32_e32 v0, 3, v13
	v_lshrrev_b32_e32 v5, 2, v4
	v_lshlrev_b32_e32 v6, 1, v4
	v_and_b32_e32 v3, 0xc0, v3
	s_mul_hi_u32 s3, s52, 0xb00000
	s_add_u32 s2, s10, s2
	v_and_or_b32 v0, v4, s6, v0
	v_and_b32_e32 v5, 4, v5
	v_and_b32_e32 v6, 24, v6
	v_sub_u32_e32 v2, v2, v3
	s_addc_u32 s3, s11, s3
	s_ashr_i32 s5, s4, 8
	s_lshl_b32 s31, s30, 10
	v_or3_b32 v0, v0, v5, v6
	v_lshlrev_b32_e32 v5, 5, v14
	v_ashrrev_i16_sdwa v2, v236, sext(v2) dst_sel:DWORD dst_unused:UNUSED_PAD src0_sel:DWORD src1_sel:BYTE_0
	v_readlane_b32 s6, v254, 15
	v_and_b32_e32 v5, 32, v5
	v_bfe_i32 v15, v2, 0, 16
	v_readlane_b32 s7, v254, 16
	s_add_u32 s24, s2, s6
	v_add_lshl_u32 v2, v5, v15, 1
	s_addc_u32 s25, s3, s7
	s_add_i32 s33, s31, 0
	v_lshl_add_u32 v0, v0, 11, v2
	s_add_i32 m0, s33, 0x10000
	v_readlane_b32 s6, v254, 13
	global_load_lds_dwordx4 v0, s[24:25]
	s_add_i32 m0, s33, 0x12000
	v_readlane_b32 s7, v254, 14
	s_add_u32 s26, s0, s6
	s_addc_u32 s27, s1, s7
	s_add_u32 s6, s24, 0x40000
	global_load_lds_dwordx4 v130, s[24:25]
	s_addc_u32 s7, s25, 0
	s_add_i32 m0, s33, 0x14000
	s_add_i32 s34, s33, 0x2000
	global_load_lds_dwordx4 v0, s[6:7]
	s_add_i32 m0, s33, 0x16000
	v_lshl_add_u32 v134, v4, 11, v2
	global_load_lds_dwordx4 v130, s[6:7]
	s_mov_b32 m0, s33
	s_add_u32 s6, s26, 0x40000
	global_load_lds_dwordx4 v134, s[26:27]
	s_mov_b32 m0, s34
	s_addc_u32 s7, s27, 0
	s_add_i32 s35, s33, 0x4000
	global_load_lds_dwordx4 v132, s[26:27]
	s_mov_b32 m0, s35
	s_add_i32 s36, s33, 0x6000
	global_load_lds_dwordx4 v134, s[6:7]
	s_mov_b32 m0, s36
	v_mov_b32_e32 v131, v1
	global_load_lds_dwordx4 v132, s[6:7]
	v_mov_b32_e32 v135, v1
	v_mov_b32_e32 v133, v1
	s_cmp_eq_u32 s5, 1
	v_lshl_add_u64 v[8:9], s[24:25], 0, v[0:1]
	v_lshl_add_u64 v[6:7], s[24:25], 0, v[130:131]
	v_lshl_add_u64 v[2:3], s[26:27], 0, v[134:135]
	s_cselect_b64 s[14:15], -1, 0
	s_cmp_lg_u32 s5, 1
	v_lshl_add_u64 v[4:5], s[26:27], 0, v[132:133]
	s_cbranch_scc1 .LBB0_392
	s_barrier
